# v19 + static priority raise for waves 0-3 during the SGU phase
# baseline (speedup 1.0000x reference)
; __device__ __forceinline__ void sgu_phase(LAS unsigned char* lds, const bf16_t* U, const bf16_t* GV, const bf16_t* SZ, const float* stats, const float* vg, const float* vb,
;                                           const bf16_t* wsb, const float* b_s, bf16_t* Y, int G, int bid) {
;     ...
;     const int tid = threadIdx.x, wid = tid >> 6, lane = tid & 63, fr = lane & 15, fq = lane >> 4;
;     const bool xmap = (G == 256);
;     for (int itl = bid; itl < 1024; itl += G) {
;         const int it = xmap ? ((bid & 7) * 128 + (bid >> 3) + 32 * (itl >> 8)) : itl;
;         const int ci = it >> 4, g = it & 15, row0 = ci * 128;
;         __syncthreads();
;         if (tid < 128) {
;             const float* sp = stats + (size_t)(row0 + tid) * 64; float s = 0.f, ss = 0.f;
; #pragma unroll
;             for (int i = 0; i < 16; ++i) { const f32x4 q = *(const f32x4*)(sp + i * 4); s += q[0] + q[2]; ss += q[1] + q[3]; }
;             const float mean = s * (1.0f / DM), var = ss * (1.0f / DM) - mean * mean;
;             rstat[tid] = (f32x2){mean, rsqrtf(var + 1e-5f)};
;         }
;         __syncthreads();
; #pragma unroll
;         for (int i = 0; i < 4; ++i) {
;             const int id = tid + 512 * i, r = id >> 4, cc = id & 15;
;             const u32x4 w = *(const u32x4*)(GV + (size_t)(row0 + r) * DM + g * 128 + cc * 8);
;             const f32x2 st = rstat[r];
;             const f32x4 g0 = *(const f32x4*)(vg + g * 128 + cc * 8), g1 = *(const f32x4*)(vg + g * 128 + cc * 8 + 4);
;             const f32x4 b0 = *(const f32x4*)(vb + g * 128 + cc * 8), b1 = *(const f32x4*)(vb + g * 128 + cc * 8 + 4);
;             float f[8] = {bf_lo(w.x), bf_hi(w.x), bf_lo(w.y), bf_hi(w.y), bf_lo(w.z), bf_hi(w.z), bf_lo(w.w), bf_hi(w.w)};
; #pragma unroll
;             for (int j = 0; j < 8; ++j) {
;                 const float gg = j < 4 ? g0[j & 3] : g1[j & 3], bb = j < 4 ? b0[j & 3] : b1[j & 3];
;                 const float vn = (f[j] - st.x) * st.y * gg + bb;
;                 *(LAS bf16_t*)(vnT + (cc * 8 + j) * VST + (((r >> 3) ^ cc) << 4) + (r & 7) * 2) = (bf16_t)(cvt_pk_bf16(vn, 0.f) & 0xffffu);
;             }
;         }
;         __syncthreads();
;         f32x4 acc[8];
; #pragma unroll
;         for (int ct = 0; ct < 8; ++ct) acc[ct] = (f32x4){0.f, 0.f, 0.f, 0.f};
;         const bf16_t* wrow = wsb + ((size_t)g * 128 + wid * 16 + fr) * 128 + fq * 8;
.LBB0_232:
	s_cmp_lt_i32 s42, 3
	s_cselect_b64 s[0:1], -1, 0
	s_and_b64 s[4:5], s[0:1], s[4:5]
	s_andn2_b64 vcc, exec, s[4:5]
	s_cbranch_vccnz .LBB0_241
	s_cmpk_gt_i32 s2, 0x3ff
	s_cbranch_scc1 .LBB0_240
	v_readfirstlane_b32 s98, v164
	s_bitcmp0_b32 s98, 8
	s_cbranch_scc0 .Lsgu_np
	s_setprio 1
.Lsgu_np:
	s_cmpk_eq_i32 s34, 0x100
	s_waitcnt vmcnt(0)
	v_add_u32_e32 v5, 0x200, v164
	s_cselect_b64 s[6:7], -1, 0
	s_lshl_b32 s0, s2, 7
	v_lshrrev_b32_e32 v6, 7, v5
	s_and_b32 s3, s0, 0x380
	s_ashr_i32 s0, s2, 3
	v_lshrrev_b32_e32 v50, 4, v5
	v_bitop3_b32 v6, v6, v164, 15 bitop3:0x78
	v_lshrrev_b32_e32 v5, 3, v5
	s_add_i32 s3, s3, s0
	s_and_b32 s3, s2, 7
	s_lshl_b32 s3, s3, 7
	s_bfe_u32 s0, s2, 0x20003
	s_lshl_b32 s0, s0, 5
	s_add_i32 s3, s3, s0
	s_lshr_b32 s0, s2, 5
	s_lshl_b32 s0, s0, 1
	s_add_i32 s3, s3, s0
	s_movk_i32 s0, 0x80
	v_lshlrev_b32_e32 v6, 4, v6
	v_and_b32_e32 v5, 14, v5
	v_and_b32_e32 v0, 15, v164
	v_cmp_gt_u32_e32 vcc, s0, v164
	v_lshrrev_b32_e32 v1, 2, v164
	s_movk_i32 s0, 0xf0
	v_add3_u32 v5, 0, v6, v5
	v_or_b32_e32 v6, 0x400, v164
	v_and_or_b32 v47, v1, s0, v0
	v_lshrrev_b32_e32 v1, 7, v164
	v_lshrrev_b32_e32 v52, 4, v6
	v_lshrrev_b32_e32 v6, 7, v6
	v_bitop3_b32 v2, v1, v164, 15 bitop3:0x78
	v_lshrrev_b32_e32 v3, 3, v164
	v_bitop3_b32 v6, v6, v164, 15 bitop3:0x78
	v_lshlrev_b32_e32 v2, 4, v2
	v_and_b32_e32 v3, 14, v3
	v_lshlrev_b32_e32 v6, 4, v6
	v_add3_u32 v2, 0, v2, v3
	v_add3_u32 v3, 0, v6, v3
	v_add_u32_e32 v6, 0x600, v164
	v_lshlrev_b32_e32 v32, 4, v0
	v_mov_b32_e32 v33, 0
	v_lshrrev_b32_e32 v7, 7, v6
	v_bfe_u32 v41, v164, 4, 2
	v_lshl_add_u64 v[34:35], s[10:11], 0, v[32:33]
	v_lshlrev_b32_e32 v32, 5, v0
	v_lshrrev_b32_e32 v54, 4, v6
	v_bitop3_b32 v7, v7, v164, 15 bitop3:0x78
	v_lshrrev_b32_e32 v6, 3, v6
	v_lshl_add_u64 v[36:37], s[22:23], 0, v[32:33]
	v_lshl_add_u64 v[38:39], s[24:25], 0, v[32:33]
	v_lshlrev_b32_e32 v7, 4, v7
	v_and_b32_e32 v6, 14, v6
	s_movk_i32 s0, 0x110
	v_lshlrev_b32_e32 v32, 4, v41
	v_bfe_u32 v48, v164, 3, 1
	v_mul_u32_u24_e32 v4, 0x880, v0
	v_add3_u32 v6, 0, v7, v6
	v_mad_u32_u24 v56, v0, s0, 0
	v_add_u32_e32 v64, 1, v1
	v_lshl_add_u64 v[0:1], s[40:41], 0, v[32:33]
	s_mov_b64 s[0:1], 0x3c80000
	s_mov_b32 s19, 0
	v_lshl_add_u32 v46, v164, 3, 0
	v_lshlrev_b32_e32 v40, 2, v41
	v_lshl_add_u32 v49, v214, 3, 0
	v_lshl_add_u32 v51, v50, 3, 0
	v_lshl_add_u32 v53, v52, 3, 0
	v_lshl_add_u32 v55, v54, 3, 0
	v_or_b32_e32 v57, 2, v48
	v_or_b32_e32 v58, 4, v48
	v_or_b32_e32 v59, 6, v48
	v_or_b32_e32 v60, 8, v48
	v_or_b32_e32 v61, 10, v48
	v_or_b32_e32 v62, 12, v48
	v_or_b32_e32 v63, 14, v48
	v_lshl_add_u64 v[42:43], v[0:1], 0, s[0:1]
	s_mov_b32 s22, 0x3a000000
	s_mov_b32 s23, 0x800000
	v_add_u32_e32 v65, v2, v4
	v_add_u32_e32 v66, v5, v4
	v_add_u32_e32 v67, v3, v4
	v_add_u32_e32 v68, v6, v4
	s_mov_b32 s26, s2
